# dilated units: Q tile staged by LDS-DMA (full 128-byte lines, same image as K) and read as LDS fragments, instead of four 16-byte global loads per lane
# speedup vs baseline: 1.0094x; 1.0094x over previous
.LBB0_439:
	s_mov_b32 s79, m0
	s_mov_b32 m0, s63
	s_nop 0
	global_load_lds_dwordx4 v0, s[54:55]
	s_mov_b32 m0, s79
	s_add_i32 s79, s63, 0x2000
	s_add_i32 s78, s78, 1
	s_mov_b32 s80, m0
	s_mov_b32 m0, s79
	s_nop 0
	global_load_lds_dwordx4 v2, s[54:55]
	s_mov_b32 m0, s80
	s_add_u32 s54, s54, s52
	s_addc_u32 s55, s55, s53
	s_addk_i32 s63, 0x4000
	s_cmp_ge_i32 s78, s62
	s_cbranch_scc0 .LBB0_439
	s_lshl_b64 s[78:79], s[52:53], 2
	s_sub_u32 s54, s54, s78
	s_subb_u32 s55, s55, s79
	s_sub_u32 s54, s54, 0x400
	s_subb_u32 s55, s55, 0
	s_lshl_b32 s78, s57, 10
	s_add_i32 s78, s78, 0x18000
	s_mov_b32 s80, m0
	s_mov_b32 m0, s78
	s_nop 0
	global_load_lds_dwordx4 v0, s[54:55]
	s_add_u32 s54, s54, s52
	s_addc_u32 s55, s55, s53
	s_addk_i32 s78, 0x2000
	s_mov_b32 m0, s78
	s_nop 0
	global_load_lds_dwordx4 v0, s[54:55]
	s_add_u32 s54, s54, s52
	s_addc_u32 s55, s55, s53
	s_addk_i32 s78, 0x2000
	s_mov_b32 m0, s78
	s_nop 0
	global_load_lds_dwordx4 v0, s[54:55]
	s_add_u32 s54, s54, s52
	s_addc_u32 s55, s55, s53
	s_addk_i32 s78, 0x2000
	s_mov_b32 m0, s78
	s_nop 0
	global_load_lds_dwordx4 v0, s[54:55]
	s_mov_b32 m0, s80
.LBB0_440:
	s_lshl_b32 s52, s56, 8
	s_lshl_b32 s62, s57, 5
	v_and_b32_e32 v2, 31, v34
	s_add_i32 s62, s62, s52
	v_or_b32_e32 v36, s62, v2
	v_ashrrev_i32_e32 v37, 31, v36
	v_lshlrev_b64 v[4:5], s60, v[36:37]
	v_lshl_add_u64 v[130:131], v[4:5], 0, s[10:11]
	v_mov_b64_e32 v[4:5], s[40:41]
	v_lshrrev_b32_e32 v69, 5, v153
	v_mad_u64_u32 v[4:5], s[52:53], v130, s66, v[4:5]
	v_mad_i32_i24 v5, v131, s66, v5
	v_lshlrev_b32_e32 v0, 4, v69
	v_lshl_add_u64 v[4:5], v[4:5], 0, v[0:1]
	v_mov_b32_e32 v156, 0
	s_cmpk_lt_i32 s65, 0x200
	v_mov_b32_e32 v155, 0
	v_mov_b32_e32 v154, 0
	s_waitcnt vmcnt(3)
	s_waitcnt vmcnt(2)
	s_waitcnt vmcnt(1)
	s_waitcnt vmcnt(0)
	s_waitcnt vmcnt(0) lgkmcnt(0)
	s_barrier
	s_cbranch_scc0 .LBB0_461
	s_cmpk_gt_i32 s65, 0x7f
	s_mov_b64 s[52:53], -1
	s_cbranch_scc0 .LBB0_453
	s_add_i32 s52, s65, 0xff80
	s_and_b32 s10, s52, 0xffff
	s_mul_i32 s10, s10, 0xaaab
	s_lshr_b32 s10, s10, 21
	s_mul_i32 s53, s10, 48
	s_sub_i32 s52, s52, s53
	s_and_b32 s56, s52, 0xffff
	s_mov_b64 s[52:53], 0
	s_cmp_lt_u32 s56, 16
	s_mov_b32 s54, 0
	s_cbranch_scc1 .LBB0_448
	s_cmp_gt_u32 s56, 31
	s_mov_b64 s[52:53], -1
	s_cbranch_scc0 .LBB0_445
	s_sub_i32 s54, s56, 32
	s_mov_b64 s[52:53], 0

.LBB0_461:
	s_ashr_i32 s10, s62, 6
	s_addk_i32 s62, 0xff80
	s_ashr_i32 s52, s62, 6
	s_max_i32 s54, s52, s59
	s_mov_b64 s[52:53], -1
	s_cmp_le_i32 s54, s10
	v_lshlrev_b32_e32 v157, 2, v69
	s_cbranch_scc0 .LBB0_470
	v_and_b32_e32 v50, 31, v153
	v_lshrrev_b32_e32 v51, 5, v153
	v_lshlrev_b32_e32 v132, 2, v51
	v_sub_u32_e32 v122, v50, v132
	v_lshrrev_b32_e32 v52, 1, v50
	v_and_b32_e32 v53, 6, v52
	v_lshlrev_b32_e32 v53, 4, v53
	v_and_b32_e32 v52, 1, v52
	v_xor_b32_e32 v52, v52, v51
	v_lshlrev_b32_e32 v52, 4, v52
	v_lshl_add_u32 v124, v50, 7, v53
	v_add_u32_e32 v124, v124, v52
	v_xor_b32_e32 v134, 32, v124
	v_xor_b32_e32 v135, 64, v124
	v_xor_b32_e32 v136, 0x60, v124
	v_bfe_u32 v52, v153, 4, 1
	v_lshlrev_b32_e32 v52, 5, v52
	v_and_b32_e32 v53, 3, v153
	v_lshl_add_u32 v52, v53, 3, v52
	v_bfe_u32 v53, v153, 2, 2
	v_add_u32_e32 v53, v53, v132
	v_lshl_add_u32 v125, v53, 6, v52
	v_readfirstlane_b32 s52, v186
	s_nop 0
	s_lshr_b32 s52, s52, 6
	s_lshl_b32 s52, s52, 12
	s_add_i32 s52, s52, 0x18000
	v_add_u32_e32 v140, s52, v124
	v_xor_b32_e32 v141, 32, v140
	v_xor_b32_e32 v142, 64, v140
	v_xor_b32_e32 v143, 0x60, v140
	ds_read_b128 v[82:85], v140
	ds_read_b128 v[86:89], v141
	ds_read_b128 v[90:93], v142
	ds_read_b128 v[94:97], v143
	s_add_i32 s62, s62, 0x80
	s_lshr_b32 s54, s62, 5
	s_sub_i32 s55, 4, s54
	s_max_i32 s55, s55, 0
	s_add_i32 s54, s54, s55
	s_add_i32 s54, s54, -4
	s_lshr_b32 s52, s54, 1
	s_sub_i32 s52, s52, s59
	s_lshl_b32 s52, s52, 14
	s_and_b32 s53, s54, 1
	s_lshl_b32 s56, s53, 12
	s_add_i32 s56, s56, s52
	v_add_u32_e32 v140, s56, v124
	v_add_u32_e32 v141, s56, v134
	v_add_u32_e32 v142, s56, v135
	v_add_u32_e32 v143, s56, v136
	ds_read_b128 v[50:53], v140
	ds_read_b128 v[54:57], v141
	ds_read_b128 v[58:61], v142
	ds_read_b128 v[62:65], v143
	s_add_i32 s61, s61, 1
	v_cvt_f32_i32_e32 v144, s61
	v_exp_f32_e64 v144, -v144
	s_lshl_b32 s53, 1, s60
	v_cvt_f32_ubyte0_e32 v145, s53
	s_nop 0
	v_mul_f32_e32 v144, v144, v145
	v_mul_f32_e32 v126, 0x3fb8aa3b, v144
	v_mov_b32_e32 v187, 0
	v_mov_b32_e32 v188, v126
	v_mul_f32_e32 v189, 0x40000000, v126
	v_mul_f32_e32 v190, 0x40400000, v126
	v_mul_f32_e32 v191, 0x41000000, v126
	v_mul_f32_e32 v192, 0x41100000, v126
	v_mul_f32_e32 v193, 0x41200000, v126
	v_mul_f32_e32 v194, 0x41300000, v126
	v_mul_f32_e32 v195, 0x41800000, v126
	v_mul_f32_e32 v196, 0x41880000, v126
	v_mul_f32_e32 v197, 0x41900000, v126
	v_mul_f32_e32 v198, 0x41980000, v126
	v_mul_f32_e32 v199, 0x41c00000, v126
	v_mul_f32_e32 v200, 0x41c80000, v126
	v_mul_f32_e32 v201, 0x41d00000, v126
	v_mul_f32_e32 v202, 0x41d80000, v126
	v_cmp_ge_i32_e64 s[52:53], 0, v122
	v_cmp_ge_i32_e64 s[56:57], 1, v122
	v_cmp_ge_i32_e64 s[62:63], 2, v122
	v_cmp_ge_i32_e64 s[10:11], 3, v122
	s_nop 1
	v_cndmask_b32_e64 v203, v177, v187, s[52:53]
	v_cndmask_b32_e64 v204, v177, v188, s[56:57]
	v_cndmask_b32_e64 v205, v177, v189, s[62:63]
	v_cndmask_b32_e64 v206, v177, v190, s[10:11]
	v_cmp_ge_i32_e64 s[52:53], 8, v122
	v_cmp_ge_i32_e64 s[56:57], 9, v122
	v_cmp_ge_i32_e64 s[62:63], 10, v122
	v_cmp_ge_i32_e64 s[10:11], 11, v122
	s_nop 1
	v_cndmask_b32_e64 v207, v177, v191, s[52:53]
	v_cndmask_b32_e64 v208, v177, v192, s[56:57]
	v_cndmask_b32_e64 v209, v177, v193, s[62:63]
	v_cndmask_b32_e64 v210, v177, v194, s[10:11]
	v_cmp_ge_i32_e64 s[52:53], 16, v122
	v_cmp_ge_i32_e64 s[56:57], 17, v122
	v_cmp_ge_i32_e64 s[62:63], 18, v122
	v_cmp_ge_i32_e64 s[10:11], 19, v122
	s_nop 1
	v_cndmask_b32_e64 v211, v177, v195, s[52:53]
	v_cndmask_b32_e64 v212, v177, v196, s[56:57]
	v_cndmask_b32_e64 v213, v177, v197, s[62:63]
	v_cndmask_b32_e64 v214, v177, v198, s[10:11]
	v_cmp_ge_i32_e64 s[52:53], 24, v122
	v_cmp_ge_i32_e64 s[56:57], 25, v122
	v_cmp_ge_i32_e64 s[62:63], 26, v122
	v_cmp_ge_i32_e64 s[10:11], 27, v122
	s_nop 1
	v_cndmask_b32_e64 v215, v177, v199, s[52:53]
	v_cndmask_b32_e64 v216, v177, v200, s[56:57]
	v_cndmask_b32_e64 v217, v177, v201, s[62:63]
	v_cndmask_b32_e64 v218, v177, v202, s[10:11]
	v_cmp_le_i32_e64 s[52:53], 0, v122
	v_cmp_le_i32_e64 s[56:57], 1, v122
	v_cmp_le_i32_e64 s[62:63], 2, v122
	v_cmp_le_i32_e64 s[10:11], 3, v122
	s_nop 1
	v_cndmask_b32_e64 v219, v177, v187, s[52:53]
	v_cndmask_b32_e64 v220, v177, v188, s[56:57]
	v_cndmask_b32_e64 v221, v177, v189, s[62:63]
	v_cndmask_b32_e64 v222, v177, v190, s[10:11]
	v_cmp_le_i32_e64 s[52:53], 8, v122
	v_cmp_le_i32_e64 s[56:57], 9, v122
	v_cmp_le_i32_e64 s[62:63], 10, v122
	v_cmp_le_i32_e64 s[10:11], 11, v122
	s_nop 1
	v_cndmask_b32_e64 v223, v177, v191, s[52:53]
	v_cndmask_b32_e64 v224, v177, v192, s[56:57]
	v_cndmask_b32_e64 v225, v177, v193, s[62:63]
	v_cndmask_b32_e64 v226, v177, v194, s[10:11]
	v_cmp_le_i32_e64 s[52:53], 16, v122
	v_cmp_le_i32_e64 s[56:57], 17, v122
	v_cmp_le_i32_e64 s[62:63], 18, v122
	v_cmp_le_i32_e64 s[10:11], 19, v122
	s_nop 1
	v_cndmask_b32_e64 v227, v177, v195, s[52:53]
	v_cndmask_b32_e64 v228, v177, v196, s[56:57]
	v_cndmask_b32_e64 v229, v177, v197, s[62:63]
	v_cndmask_b32_e64 v230, v177, v198, s[10:11]
	v_cmp_le_i32_e64 s[52:53], 24, v122
	v_cmp_le_i32_e64 s[56:57], 25, v122
	v_cmp_le_i32_e64 s[62:63], 26, v122
	v_cmp_le_i32_e64 s[10:11], 27, v122
	s_nop 1
	v_cndmask_b32_e64 v231, v177, v199, s[52:53]
	v_cndmask_b32_e64 v232, v177, v200, s[56:57]
	v_cndmask_b32_e64 v233, v177, v201, s[62:63]
	v_cndmask_b32_e64 v234, v177, v202, s[10:11]
	s_mov_b32 s11, 0
	v_mov_b32_e32 v2, 0
	v_mov_b32_e32 v3, 0
	v_mov_b32_e32 v4, 0
	v_mov_b32_e32 v5, 0
	v_mov_b32_e32 v6, 0
	v_mov_b32_e32 v7, 0
	v_mov_b32_e32 v8, 0
	v_mov_b32_e32 v9, 0
	v_mov_b32_e32 v10, 0
	v_mov_b32_e32 v11, 0
	v_mov_b32_e32 v12, 0
	v_mov_b32_e32 v13, 0
	v_mov_b32_e32 v14, 0
	v_mov_b32_e32 v15, 0
	v_mov_b32_e32 v16, 0
	v_mov_b32_e32 v17, 0
	v_mov_b32_e32 v18, 0
	v_mov_b32_e32 v19, 0
	v_mov_b32_e32 v20, 0
	v_mov_b32_e32 v21, 0
	v_mov_b32_e32 v22, 0
	v_mov_b32_e32 v23, 0
	v_mov_b32_e32 v24, 0
	v_mov_b32_e32 v25, 0
	v_mov_b32_e32 v26, 0
	v_mov_b32_e32 v27, 0
	v_mov_b32_e32 v28, 0
	v_mov_b32_e32 v29, 0
	v_mov_b32_e32 v30, 0
	v_mov_b32_e32 v31, 0
	v_mov_b32_e32 v32, 0
	v_mov_b32_e32 v33, 0
	v_mov_b32_e32 v138, 0
	v_mov_b32_e32 v139, 0
	s_mov_b32 s63, 1
